# all v_mov_b64 vpair,vpair replaced by two v_mov_b32 (test whether 64-bit moves issue slowly)
# baseline (speedup 1.0000x reference)
.LBB0_23:
	s_or_b64 exec, exec, s[8:9]
	v_lshl_add_u32 v2, s12, 2, v26
	v_lshlrev_b64 v[24:25], 12, v[2:3]
	v_lshl_add_u64 v[68:69], v[18:19], 0, v[24:25]
	global_load_dwordx4 v[80:83], v[10:11], off
	global_load_dwordx4 v[84:87], v[68:69], off
	global_load_dwordx4 v[88:91], v[68:69], off offset:1024
	global_load_dwordx4 v[92:95], v[10:11], off offset:1024
	global_load_dwordx4 v[96:99], v[68:69], off offset:2048
	global_load_dwordx4 v[100:103], v[10:11], off offset:2048
	global_load_dwordx4 v[104:107], v[68:69], off offset:3072
	global_load_dwordx4 v[108:111], v[10:11], off offset:3072
	v_lshl_add_u64 v[112:113], v[2:3], 2, s[62:63]
	global_load_dword v114, v[112:113], off
	s_waitcnt vmcnt(0)
	v_mov_b32_e32 v52, v80
	v_mov_b32_e32 v53, v81
	v_mov_b32_e32 v54, v82
	v_mov_b32_e32 v55, v83
	v_mov_b32_e32 v56, v84
	v_mov_b32_e32 v57, v85
	v_mov_b32_e32 v58, v86
	v_mov_b32_e32 v59, v87
	v_lshlrev_b64 v[24:25], 11, v[2:3]
	v_lshl_add_u64 v[24:25], v[20:21], 0, v[24:25]
	v_cmp_lt_i32_e32 vcc, v39, v38
	v_pk_mul_f32 v[54:55], v[58:59], v[54:55]
	v_pk_mul_f32 v[52:53], v[56:57], v[52:53]
	v_and_b32_sdwa v60, v55, v47 dst_sel:DWORD dst_unused:UNUSED_PAD src0_sel:WORD_1 src1_sel:DWORD
	v_and_b32_sdwa v51, v52, v47 dst_sel:DWORD dst_unused:UNUSED_PAD src0_sel:WORD_1 src1_sel:DWORD
	v_and_b32_sdwa v61, v53, v47 dst_sel:DWORD dst_unused:UNUSED_PAD src0_sel:WORD_1 src1_sel:DWORD
	v_and_b32_sdwa v23, v54, v47 dst_sel:DWORD dst_unused:UNUSED_PAD src0_sel:WORD_1 src1_sel:DWORD
	v_add3_u32 v51, v52, v51, s3
	v_add3_u32 v52, v55, v60, s3
	v_add3_u32 v53, v53, v61, s3
	v_add3_u32 v23, v54, v23, s3
	v_and_b32_e32 v52, 0xffff0000, v52
	v_and_b32_e32 v54, 0xffff0000, v53
	v_or_b32_sdwa v53, v52, v23 dst_sel:DWORD dst_unused:UNUSED_PAD src0_sel:DWORD src1_sel:WORD_1
	v_or_b32_sdwa v52, v54, v51 dst_sel:DWORD dst_unused:UNUSED_PAD src0_sel:DWORD src1_sel:WORD_1
	global_store_dwordx2 v[24:25], v[52:53], off
	v_mov_b32_e32 v52, v88
	v_mov_b32_e32 v53, v89
	v_mov_b32_e32 v54, v90
	v_mov_b32_e32 v55, v91
	s_nop 0
	v_mov_b32_e32 v60, v92
	v_mov_b32_e32 v61, v93
	v_mov_b32_e32 v62, v94
	v_mov_b32_e32 v63, v95
	v_pk_mul_f32 v[56:57], v[56:57], v[56:57]
	v_pk_mul_f32 v[58:59], v[58:59], v[58:59]
	v_add_f32_e32 v56, v56, v57
	v_add_f32_e32 v56, v56, v58
	v_add_f32_e32 v56, v56, v59
	v_pk_mul_f32 v[62:63], v[54:55], v[62:63]
	v_pk_mul_f32 v[60:61], v[52:53], v[60:61]
	v_and_b32_sdwa v64, v63, v47 dst_sel:DWORD dst_unused:UNUSED_PAD src0_sel:WORD_1 src1_sel:DWORD
	v_and_b32_sdwa v51, v60, v47 dst_sel:DWORD dst_unused:UNUSED_PAD src0_sel:WORD_1 src1_sel:DWORD
	v_and_b32_sdwa v65, v61, v47 dst_sel:DWORD dst_unused:UNUSED_PAD src0_sel:WORD_1 src1_sel:DWORD
	v_and_b32_sdwa v23, v62, v47 dst_sel:DWORD dst_unused:UNUSED_PAD src0_sel:WORD_1 src1_sel:DWORD
	v_add3_u32 v51, v60, v51, s3
	v_add3_u32 v60, v63, v64, s3
	v_add3_u32 v61, v61, v65, s3
	v_add3_u32 v23, v62, v23, s3
	v_and_b32_e32 v60, 0xffff0000, v60
	v_and_b32_e32 v62, 0xffff0000, v61
	v_or_b32_sdwa v61, v60, v23 dst_sel:DWORD dst_unused:UNUSED_PAD src0_sel:DWORD src1_sel:WORD_1
	v_or_b32_sdwa v60, v62, v51 dst_sel:DWORD dst_unused:UNUSED_PAD src0_sel:DWORD src1_sel:WORD_1
	global_store_dwordx2 v[24:25], v[60:61], off offset:512
	v_mov_b32_e32 v60, v96
	v_mov_b32_e32 v61, v97
	v_mov_b32_e32 v62, v98
	v_mov_b32_e32 v63, v99
	s_nop 0
	v_mov_b32_e32 v64, v100
	v_mov_b32_e32 v65, v101
	v_mov_b32_e32 v66, v102
	v_mov_b32_e32 v67, v103
	v_pk_mul_f32 v[52:53], v[52:53], v[52:53]
	v_pk_mul_f32 v[54:55], v[54:55], v[54:55]
	v_add_f32_e32 v52, v52, v53
	v_add_f32_e32 v52, v52, v54
	v_add_f32_e32 v52, v52, v55
	v_add_f32_e32 v56, v56, v52
	v_pk_mul_f32 v[54:55], v[60:61], v[60:61]
	v_pk_mul_f32 v[66:67], v[62:63], v[66:67]
	v_pk_mul_f32 v[64:65], v[60:61], v[64:65]
	v_and_b32_sdwa v70, v67, v47 dst_sel:DWORD dst_unused:UNUSED_PAD src0_sel:WORD_1 src1_sel:DWORD
	v_and_b32_sdwa v51, v64, v47 dst_sel:DWORD dst_unused:UNUSED_PAD src0_sel:WORD_1 src1_sel:DWORD
	v_and_b32_sdwa v71, v65, v47 dst_sel:DWORD dst_unused:UNUSED_PAD src0_sel:WORD_1 src1_sel:DWORD
	v_and_b32_sdwa v23, v66, v47 dst_sel:DWORD dst_unused:UNUSED_PAD src0_sel:WORD_1 src1_sel:DWORD
	v_add3_u32 v51, v64, v51, s3
	v_add3_u32 v64, v67, v70, s3
	v_add3_u32 v65, v65, v71, s3
	v_add3_u32 v23, v66, v23, s3
	v_and_b32_e32 v64, 0xffff0000, v64
	v_and_b32_e32 v66, 0xffff0000, v65
	v_or_b32_sdwa v65, v64, v23 dst_sel:DWORD dst_unused:UNUSED_PAD src0_sel:DWORD src1_sel:WORD_1
	v_or_b32_sdwa v64, v66, v51 dst_sel:DWORD dst_unused:UNUSED_PAD src0_sel:DWORD src1_sel:WORD_1
	global_store_dwordx2 v[24:25], v[64:65], off offset:1024
	v_mov_b32_e32 v64, v104
	v_mov_b32_e32 v65, v105
	v_mov_b32_e32 v66, v106
	v_mov_b32_e32 v67, v107
	s_nop 0
	v_mov_b32_e32 v68, v108
	v_mov_b32_e32 v69, v109
	v_mov_b32_e32 v70, v110
	v_mov_b32_e32 v71, v111
	v_pk_mul_f32 v[52:53], v[62:63], v[62:63]
	v_add_f32_e32 v54, v54, v55
	v_add_f32_e32 v52, v54, v52
	v_add_f32_e32 v52, v52, v53
	v_add_f32_e32 v56, v56, v52
	v_cndmask_b32_e32 v23, v37, v39, vcc
	v_lshlrev_b32_e32 v23, 2, v23
	v_cmp_lt_i32_e32 vcc, v40, v38
	v_pk_mul_f32 v[54:55], v[64:65], v[64:65]
	v_pk_mul_f32 v[52:53], v[66:67], v[66:67]
	v_add_f32_e32 v54, v54, v55
	v_add_f32_e32 v52, v54, v52
	v_add_f32_e32 v52, v52, v53
	v_add_f32_e32 v52, v56, v52
	ds_bpermute_b32 v23, v23, v52
	v_cndmask_b32_e32 v51, v37, v40, vcc
	v_lshlrev_b32_e32 v51, 2, v51
	v_cmp_lt_i32_e32 vcc, v41, v38
	s_waitcnt lgkmcnt(0)
	v_add_f32_e32 v23, v52, v23
	ds_bpermute_b32 v51, v51, v23
	v_cndmask_b32_e32 v72, v37, v41, vcc
	v_lshlrev_b32_e32 v52, 2, v72
	v_cmp_lt_i32_e32 vcc, v42, v38
	s_waitcnt lgkmcnt(0)
	v_add_f32_e32 v23, v23, v51
	ds_bpermute_b32 v51, v52, v23
	v_cndmask_b32_e32 v53, v37, v42, vcc
	v_lshlrev_b32_e32 v57, 2, v53
	v_cmp_lt_i32_e32 vcc, v43, v38
	v_pk_mul_f32 v[52:53], v[66:67], v[70:71]
	s_waitcnt lgkmcnt(0)
	v_add_f32_e32 v23, v23, v51
	ds_bpermute_b32 v51, v57, v23
	v_cndmask_b32_e32 v54, v37, v43, vcc
	v_lshlrev_b32_e32 v58, 2, v54
	v_cmp_lt_i32_e32 vcc, v44, v38
	v_pk_mul_f32 v[54:55], v[64:65], v[68:69]
	s_waitcnt lgkmcnt(0)
	v_add_f32_e32 v23, v23, v51
	ds_bpermute_b32 v51, v58, v23
	v_cndmask_b32_e32 v56, v37, v44, vcc
	v_and_b32_sdwa v60, v53, v47 dst_sel:DWORD dst_unused:UNUSED_PAD src0_sel:WORD_1 src1_sel:DWORD
	v_and_b32_sdwa v61, v55, v47 dst_sel:DWORD dst_unused:UNUSED_PAD src0_sel:WORD_1 src1_sel:DWORD
	v_and_b32_sdwa v59, v52, v47 dst_sel:DWORD dst_unused:UNUSED_PAD src0_sel:WORD_1 src1_sel:DWORD
	s_waitcnt lgkmcnt(0)
	v_add_f32_e32 v23, v23, v51
	v_lshlrev_b32_e32 v51, 2, v56
	ds_bpermute_b32 v51, v51, v23
	v_and_b32_sdwa v57, v54, v47 dst_sel:DWORD dst_unused:UNUSED_PAD src0_sel:WORD_1 src1_sel:DWORD
	v_add3_u32 v53, v53, v60, s3
	v_add3_u32 v55, v55, v61, s3
	v_add3_u32 v54, v54, v57, s3
	v_add3_u32 v52, v52, v59, s3
	v_and_b32_e32 v53, 0xffff0000, v53
	v_and_b32_e32 v55, 0xffff0000, v55
	v_or_b32_sdwa v53, v53, v52 dst_sel:DWORD dst_unused:UNUSED_PAD src0_sel:DWORD src1_sel:WORD_1
	v_or_b32_sdwa v52, v55, v54 dst_sel:DWORD dst_unused:UNUSED_PAD src0_sel:DWORD src1_sel:WORD_1
	global_store_dwordx2 v[24:25], v[52:53], off offset:1536
	s_and_saveexec_b64 s[8:9], s[4:5]
	s_cbranch_execz .LBB0_25
	v_lshl_add_u64 v[24:25], v[2:3], 2, s[16:17]
	v_add_co_u32_e32 v52, vcc, 0x20000, v24
	s_waitcnt lgkmcnt(0)
	v_add_f32_e32 v23, v23, v51
	v_addc_co_u32_e32 v53, vcc, 0, v25, vcc
	global_store_dword v[52:53], v3, off
	v_add_co_u32_e32 v52, vcc, 0x40000, v24
	global_store_dword v[24:25], v23, off
	s_nop 0
	v_addc_co_u32_e32 v53, vcc, 0, v25, vcc
	v_add_co_u32_e32 v24, vcc, 0x60000, v24
	global_store_dword v[52:53], v3, off
	s_nop 0
	v_addc_co_u32_e32 v25, vcc, 0, v25, vcc
	global_store_dword v[24:25], v3, off

.LBB0_190:
	s_or_b64 exec, exec, s[28:29]
	s_lshl_b32 s29, s38, 3
	v_readfirstlane_b32 s28, v147
	s_sub_i32 s46, 0xff8, s29
	s_and_b64 vcc, exec, s[26:27]
	s_lshr_b32 s47, s28, 6
	s_cbranch_vccnz .LBB0_196
	s_sub_i32 s29, 0x1018, s29
	s_lshr_b32 s34, s29, 5
	s_cmp_ge_u32 s47, s34
	s_cbranch_scc1 .LBB0_196
	s_add_i32 s29, s46, s3
	v_or_b32_e32 v150, s29, v168
	v_lshlrev_b64 v[2:3], 10, v[150:151]
	v_lshl_add_u64 v[2:3], v[152:153], 0, v[2:3]
	v_add_co_u32_e32 v6, vcc, 0x1000, v2
	v_or_b32_e32 v150, s29, v170
	global_load_dwordx4 v[34:37], v[2:3], off
	global_load_dwordx4 v[38:41], v[2:3], off offset:32
	global_load_dwordx4 v[42:45], v[2:3], off offset:64
	global_load_dwordx4 v[46:49], v[2:3], off offset:96
	v_addc_co_u32_e32 v7, vcc, 0, v3, vcc
	v_lshlrev_b64 v[2:3], 5, v[150:151]
	v_lshl_add_u64 v[2:3], s[64:65], 0, v[2:3]
	global_load_dwordx4 v[50:53], v[6:7], off
	global_load_dwordx4 v[54:57], v[6:7], off offset:32
	global_load_dwordx4 v[58:61], v[2:3], off offset:48
	global_load_dwordx4 v[62:65], v[2:3], off offset:32
	global_load_dwordx4 v[66:69], v[2:3], off offset:16
	global_load_dwordx4 v[70:73], v[2:3], off
	global_load_dwordx4 v[74:77], v[2:3], off offset:176
	global_load_dwordx4 v[78:81], v[2:3], off offset:160
	global_load_dwordx4 v[82:85], v[2:3], off offset:144
	global_load_dwordx4 v[86:89], v[2:3], off offset:128
	s_lshl_b32 s38, s47, 5
	s_lshl_b64 s[42:43], s[38:39], 7
	v_lshl_add_u64 v[8:9], v[154:155], 0, s[42:43]
	global_load_dwordx4 v[118:121], v[8:9], off offset:64
	global_load_dwordx4 v[114:117], v[8:9], off offset:96
	global_load_dwordx4 v[2:5], v[8:9], off
	global_load_dwordx4 v[122:125], v[8:9], off offset:32
	global_load_dwordx4 v[90:93], v[6:7], off offset:64
	global_load_dwordx4 v[94:97], v[6:7], off offset:96
	s_lshl_b64 s[28:29], s[28:29], 6
	s_and_b32 s29, s29, 63
	s_and_b32 s28, s28, 0xfffff000
	v_or_b32_e32 v128, s46, v170
	v_or_b32_e32 v129, s46, v171
	v_or_b32_e32 v130, s46, v172
	v_or_b32_e32 v131, s46, v173
	v_lshl_add_u32 v132, s47, 6, v192
	s_mov_b32 s35, s47
	v_or_b32_e32 v133, s38, v149
	v_lshl_add_u64 v[126:127], v[164:165], 0, s[28:29]
	s_waitcnt vmcnt(5)
	v_mov_b32_e32 v102, v118
	v_mov_b32_e32 v103, v119
	s_waitcnt vmcnt(4)
	v_mov_b32_e32 v98, v114
	v_mov_b32_e32 v99, v115
	s_waitcnt vmcnt(3)
	v_mov_b32_e32 v113, v5
	v_mov_b32_e32 v112, v4
	s_waitcnt vmcnt(2)
	v_mov_b32_e32 v106, v122
	v_mov_b32_e32 v107, v123
	v_mov_b32_e32 v100, v116
	v_mov_b32_e32 v101, v117
	v_mov_b32_e32 v104, v120
	v_mov_b32_e32 v105, v121
	v_mov_b32_e32 v108, v124
	v_mov_b32_e32 v109, v125
	v_mov_b32_e32 v111, v3
	v_mov_b32_e32 v110, v2
	s_branch .LBB0_194
.LBB0_193:
	v_mfma_f32_32x32x16_bf16 v[18:33], v[34:37], v[2:5], 0
	s_mov_b64 s[42:43], 0x4000
	v_lshl_add_u64 v[126:127], v[126:127], 0, s[42:43]
	v_mfma_f32_32x32x16_bf16 v[18:33], v[38:41], v[122:125], v[18:33]
	v_mfma_f32_32x32x16_bf16 v[2:17], v[50:53], v[2:5], 0
	v_mfma_f32_32x32x16_bf16 v[18:33], v[42:45], v[118:121], v[18:33]
	v_mfma_f32_32x32x16_bf16 v[2:17], v[54:57], v[122:125], v[2:17]
	s_waitcnt vmcnt(2)
	v_mov_b32_e32 v125, v109
	v_mov_b32_e32 v124, v108
	v_mov_b32_e32 v123, v107
	v_mov_b32_e32 v122, v106
	v_mfma_f32_32x32x16_bf16 v[18:33], v[46:49], v[114:117], v[18:33]
	s_waitcnt vmcnt(1)
	v_mfma_f32_32x32x16_bf16 v[2:17], v[90:93], v[118:121], v[2:17]
	s_nop 9
	s_nop 0
	s_nop 0
	s_nop 0
	s_nop 0
	v_max_f32_e32 v18, 0, v18
	v_max_f32_e32 v26, 0, v26
	v_max_f32_e32 v19, 0, v19
	v_max_f32_e32 v27, 0, v27
	v_pk_mul_f32 v[18:19], v[70:71], v[18:19]
	v_pk_mul_f32 v[26:27], v[62:63], v[26:27]
	s_nop 0
	s_nop 0
	s_nop 0
	s_nop 0
	s_waitcnt vmcnt(0)
	v_mfma_f32_32x32x16_bf16 v[2:17], v[94:97], v[114:117], v[2:17]
	v_max_f32_e32 v20, 0, v20
	v_max_f32_e32 v28, 0, v28
	v_max_f32_e32 v21, 0, v21
	v_max_f32_e32 v29, 0, v29
	v_mov_b32_e32 v114, v26
	v_mov_b32_e32 v115, v18
	v_pk_mul_f32 v[20:21], v[72:73], v[20:21]
	v_pk_mul_f32 v[28:29], v[64:65], v[28:29]
	s_nop 0
	s_nop 0
	s_nop 0
	s_nop 0
	v_pk_add_f32 v[114:115], v[114:115], 0 op_sel_hi:[1,0]
	v_mov_b32_e32 v18, v27
	v_max_f32_e32 v22, 0, v22
	v_max_f32_e32 v30, 0, v30
	v_max_f32_e32 v23, 0, v23
	v_max_f32_e32 v31, 0, v31
	v_pk_add_f32 v[18:19], v[18:19], v[114:115]
	v_mov_b32_e32 v26, v28
	v_mov_b32_e32 v27, v20
	v_pk_mul_f32 v[22:23], v[66:67], v[22:23]
	v_pk_mul_f32 v[30:31], v[58:59], v[30:31]
	s_nop 0
	s_nop 0
	s_nop 0
	s_nop 0
	v_pk_add_f32 v[18:19], v[26:27], v[18:19]
	v_mov_b32_e32 v20, v29
	v_max_f32_e32 v24, 0, v24
	v_max_f32_e32 v32, 0, v32
	v_max_f32_e32 v25, 0, v25
	v_max_f32_e32 v33, 0, v33
	v_pk_add_f32 v[18:19], v[20:21], v[18:19]
	v_mov_b32_e32 v20, v30
	v_mov_b32_e32 v21, v22
	v_pk_mul_f32 v[24:25], v[68:69], v[24:25]
	v_pk_mul_f32 v[32:33], v[60:61], v[32:33]
	v_pk_add_f32 v[18:19], v[20:21], v[18:19]
	v_mov_b32_e32 v22, v31
	v_pk_add_f32 v[18:19], v[22:23], v[18:19]
	v_mov_b32_e32 v20, v32
	v_mov_b32_e32 v21, v24
	v_pk_add_f32 v[18:19], v[20:21], v[18:19]
	v_mov_b32_e32 v24, v33
	v_pk_add_f32 v[18:19], v[24:25], v[18:19]
	s_nop 0
	v_pk_add_f32 v[18:19], v[18:19], 0 op_sel_hi:[1,0]
	s_nop 0
	v_bfe_u32 v20, v19, 13, 18
	v_med3_u32 v20, v20, s44, v197
	v_add_u32_e32 v21, 0x5400, v20
	v_sub_u32_e32 v20, 0x22bff, v20
	v_or_b32_e32 v21, 0x8000, v21
	v_max_u32_e32 v20, 1, v20
	v_cmp_gt_i32_e32 vcc, 0, v19
	s_nop 0
	s_nop 0
	v_cndmask_b32_e32 v19, v21, v20, vcc
	v_cmp_le_u32_e32 vcc, v133, v128
	v_max_f32_e32 v2, 0, v2
	v_max_f32_e32 v10, 0, v10
	v_cndmask_b32_e32 v19, 0, v19, vcc
	ds_write_b16 v132, v19
	v_bfe_u32 v19, v18, 13, 18
	v_med3_u32 v19, v19, s44, v197
	v_add_u32_e32 v20, 0x5400, v19
	v_sub_u32_e32 v19, 0x22bff, v19
	v_or_b32_e32 v20, 0x8000, v20
	v_max_u32_e32 v19, 1, v19
	v_cmp_gt_i32_e32 vcc, 0, v18
	v_max_f32_e32 v3, 0, v3
	v_max_f32_e32 v11, 0, v11
	v_cndmask_b32_e32 v18, v20, v19, vcc
	v_cmp_le_u32_e32 vcc, v133, v129
	v_pk_mul_f32 v[2:3], v[86:87], v[2:3]
	v_pk_mul_f32 v[10:11], v[78:79], v[10:11]
	s_nop 0
	s_nop 0
	s_nop 0
	s_nop 0
	v_cndmask_b32_e32 v18, 0, v18, vcc
	v_max_f32_e32 v4, 0, v4
	v_max_f32_e32 v12, 0, v12
	v_max_f32_e32 v5, 0, v5
	v_max_f32_e32 v13, 0, v13
	ds_write_b16 v132, v18 offset:8192
	v_mov_b32_e32 v18, v10
	v_mov_b32_e32 v19, v2
	v_pk_mul_f32 v[4:5], v[88:89], v[4:5]
	v_pk_mul_f32 v[12:13], v[80:81], v[12:13]
	s_nop 0
	s_nop 0
	s_nop 0
	s_nop 0
	v_pk_add_f32 v[18:19], v[18:19], 0 op_sel_hi:[1,0]
	v_mov_b32_e32 v2, v11
	v_max_f32_e32 v6, 0, v6
	v_max_f32_e32 v14, 0, v14
	v_max_f32_e32 v7, 0, v7
	v_max_f32_e32 v15, 0, v15
	v_pk_add_f32 v[2:3], v[2:3], v[18:19]
	v_mov_b32_e32 v10, v12
	v_mov_b32_e32 v11, v4
	v_pk_mul_f32 v[6:7], v[82:83], v[6:7]
	v_pk_mul_f32 v[14:15], v[74:75], v[14:15]
	s_nop 0
	s_nop 0
	s_nop 0
	s_nop 0
	v_pk_add_f32 v[2:3], v[10:11], v[2:3]
	v_mov_b32_e32 v4, v13
	v_max_f32_e32 v8, 0, v8
	v_max_f32_e32 v16, 0, v16
	v_max_f32_e32 v9, 0, v9
	v_max_f32_e32 v17, 0, v17
	v_pk_add_f32 v[2:3], v[4:5], v[2:3]
	v_mov_b32_e32 v4, v14
	v_mov_b32_e32 v5, v6
	v_pk_mul_f32 v[8:9], v[84:85], v[8:9]
	v_pk_mul_f32 v[16:17], v[76:77], v[16:17]
	v_pk_add_f32 v[2:3], v[4:5], v[2:3]
	v_mov_b32_e32 v6, v15
	v_pk_add_f32 v[2:3], v[6:7], v[2:3]
	v_mov_b32_e32 v4, v16
	v_mov_b32_e32 v5, v8
	v_pk_add_f32 v[2:3], v[4:5], v[2:3]
	v_mov_b32_e32 v8, v17
	v_pk_add_f32 v[2:3], v[8:9], v[2:3]
	v_mov_b32_e32 v121, v105
	v_mov_b32_e32 v120, v104
	v_pk_add_f32 v[2:3], v[2:3], 0 op_sel_hi:[1,0]
	v_mov_b32_e32 v117, v101
	v_mov_b32_e32 v116, v100
	v_bfe_u32 v4, v3, 13, 18
	v_med3_u32 v4, v4, s44, v197
	v_add_u32_e32 v5, 0x5400, v4
	v_sub_u32_e32 v4, 0x22bff, v4
	v_or_b32_e32 v5, 0x8000, v5
	v_max_u32_e32 v4, 1, v4
	v_cmp_gt_i32_e32 vcc, 0, v3
	v_mov_b32_e32 v119, v103
	v_mov_b32_e32 v118, v102
	v_mov_b32_e32 v115, v99
	v_mov_b32_e32 v114, v98
	v_cndmask_b32_e32 v3, v5, v4, vcc
	v_cmp_le_u32_e32 vcc, v133, v130
	s_nop 1
	v_cndmask_b32_e32 v3, 0, v3, vcc
	ds_write_b16 v132, v3 offset:32768
	v_bfe_u32 v3, v2, 13, 18
	v_med3_u32 v3, v3, s44, v197
	v_add_u32_e32 v4, 0x5400, v3
	v_sub_u32_e32 v3, 0x22bff, v3
	v_or_b32_e32 v4, 0x8000, v4
	v_max_u32_e32 v3, 1, v3
	v_cmp_gt_i32_e32 vcc, 0, v2
	s_nop 1
	v_cndmask_b32_e32 v2, v4, v3, vcc
	v_cmp_le_u32_e32 vcc, v133, v131
	v_add_u32_e32 v133, 0x80, v133
	s_nop 0
	v_cndmask_b32_e32 v2, 0, v2, vcc
	ds_write_b16 v132, v2 offset:40960
	v_mov_b32_e32 v2, v110
	v_mov_b32_e32 v3, v111
	v_add_u32_e32 v132, 0x100, v132
	s_andn2_b64 vcc, exec, s[28:29]
	v_mov_b32_e32 v4, v112
	v_mov_b32_e32 v5, v113
	s_cbranch_vccz .LBB0_196

.LBB0_252:
	s_or_b64 exec, exec, s[34:35]
	s_min_u32 s50, s43, 0xff
	s_lshl_b32 s51, s42, 9
	s_add_i32 s51, s51, 0x11000
	v_min_u32_e32 v18, s50, v177
	v_min_u32_e32 v19, s50, v178
	v_lshl_or_b32 v18, v18, 1, s51
	v_lshl_or_b32 v19, v19, 1, s51
	ds_read_u16 v18, v18
	ds_read_u16 v19, v19
	v_mov_b32_e32 v35, v151
	v_min_u32_e32 v50, s50, v179
	v_lshl_or_b32 v50, v50, 1, s51
	s_waitcnt lgkmcnt(1)
	v_add_lshl_u32 v150, s3, v18, 9
	s_waitcnt lgkmcnt(0)
	v_add_lshl_u32 v34, s33, v19, 9
	v_lshl_add_u64 v[30:31], v[158:159], 0, v[150:151]
	v_lshl_add_u64 v[46:47], v[158:159], 0, v[34:35]
	global_load_dwordx4 v[18:21], v[30:31], off offset:192
	global_load_dwordx4 v[22:25], v[30:31], off offset:128
	global_load_dwordx4 v[26:29], v[30:31], off offset:64
	s_nop 0
	global_load_dwordx4 v[30:33], v[30:31], off
	s_nop 0
	global_load_dwordx4 v[34:37], v[46:47], off offset:192
	global_load_dwordx4 v[38:41], v[46:47], off offset:128
	global_load_dwordx4 v[42:45], v[46:47], off offset:64
	s_nop 0
	global_load_dwordx4 v[46:49], v[46:47], off
	ds_read_u16 v51, v50
	v_min_u32_e32 v50, s50, v175
	v_lshl_or_b32 v50, v50, 1, s51
	ds_read_u16 v50, v50
	s_add_i32 s34, s50, 16
	s_waitcnt lgkmcnt(1)
	v_add_lshl_u32 v150, s3, v51, 9
	v_mov_b32_e32 v51, v151
	v_lshl_add_u64 v[52:53], v[158:159], 0, v[150:151]
	s_waitcnt lgkmcnt(0)
	v_add_lshl_u32 v50, s33, v50, 9
	v_lshl_add_u64 v[50:51], v[158:159], 0, v[50:51]
	global_load_dwordx4 v[66:69], v[52:53], off offset:192
	global_load_dwordx4 v[70:73], v[52:53], off offset:128
	global_load_dwordx4 v[90:93], v[52:53], off offset:64
	global_load_dwordx4 v[94:97], v[52:53], off
	global_load_dwordx4 v[130:133], v[50:51], off offset:192
	global_load_dwordx4 v[134:137], v[50:51], off offset:128
	global_load_dwordx4 v[138:141], v[50:51], off offset:64
	global_load_dwordx4 v[142:145], v[50:51], off
	s_lshr_b32 s42, s34, 4
	v_mov_b32_e32 v204, 0xff800000
	s_mov_b32 s43, 2
	v_mov_b32_e32 v205, v201
	v_mov_b32_e32 v206, v194
	s_waitcnt vmcnt(15)
	v_mov_b32_e32 v101, v21
	v_mov_b32_e32 v100, v20
	s_waitcnt vmcnt(14)
	v_mov_b32_e32 v105, v25
	v_mov_b32_e32 v104, v24
	s_waitcnt vmcnt(13)
	v_mov_b32_e32 v109, v29
	v_mov_b32_e32 v108, v28
	s_waitcnt vmcnt(12)
	v_mov_b32_e32 v113, v33
	v_mov_b32_e32 v112, v32
	s_waitcnt vmcnt(11)
	v_mov_b32_e32 v77, v37
	v_mov_b32_e32 v76, v36
	s_waitcnt vmcnt(10)
	v_mov_b32_e32 v81, v41
	v_mov_b32_e32 v80, v40
	s_waitcnt vmcnt(9)
	v_mov_b32_e32 v85, v45
	v_mov_b32_e32 v84, v44
	s_waitcnt vmcnt(8)
	v_mov_b32_e32 v89, v49
	v_mov_b32_e32 v88, v48
	v_mov_b32_e32 v99, v19
	v_mov_b32_e32 v98, v18
	v_mov_b32_e32 v103, v23
	v_mov_b32_e32 v102, v22
	v_mov_b32_e32 v107, v27
	v_mov_b32_e32 v106, v26
	v_mov_b32_e32 v111, v31
	v_mov_b32_e32 v110, v30
	s_waitcnt vmcnt(7)
	v_mov_b32_e32 v50, v66
	v_mov_b32_e32 v51, v67
	s_waitcnt vmcnt(6)
	v_mov_b32_e32 v54, v70
	v_mov_b32_e32 v55, v71
	s_waitcnt vmcnt(5)
	v_mov_b32_e32 v58, v90
	v_mov_b32_e32 v59, v91
	s_waitcnt vmcnt(4)
	v_mov_b32_e32 v62, v94
	v_mov_b32_e32 v63, v95
	s_waitcnt vmcnt(3)
	v_mov_b32_e32 v114, v130
	v_mov_b32_e32 v115, v131
	s_waitcnt vmcnt(2)
	v_mov_b32_e32 v118, v134
	v_mov_b32_e32 v119, v135
	s_waitcnt vmcnt(1)
	v_mov_b32_e32 v122, v138
	v_mov_b32_e32 v123, v139
	s_waitcnt vmcnt(0)
	v_mov_b32_e32 v126, v142
	v_mov_b32_e32 v127, v143
	v_mov_b32_e32 v75, v35
	v_mov_b32_e32 v74, v34
	v_mov_b32_e32 v79, v39
	v_mov_b32_e32 v78, v38
	v_mov_b32_e32 v83, v43
	v_mov_b32_e32 v82, v42
	v_mov_b32_e32 v87, v47
	v_mov_b32_e32 v86, v46
	v_mov_b32_e32 v52, v68
	v_mov_b32_e32 v53, v69
	v_mov_b32_e32 v56, v72
	v_mov_b32_e32 v57, v73
	v_mov_b32_e32 v60, v92
	v_mov_b32_e32 v61, v93
	v_mov_b32_e32 v64, v96
	v_mov_b32_e32 v65, v97
	v_mov_b32_e32 v116, v132
	v_mov_b32_e32 v117, v133
	v_mov_b32_e32 v120, v136
	v_mov_b32_e32 v121, v137
	v_mov_b32_e32 v124, v140
	v_mov_b32_e32 v125, v141
	v_mov_b32_e32 v128, v144
	v_mov_b32_e32 v129, v145
	s_add_i32 s76, s43, 2
	s_cmp_ge_u32 s76, s42
	s_cbranch_scc1 .LBB0_254

.LBB0_268:
	s_add_i32 s43, s43, 4
	v_add_u32_e32 v206, 64, v206
	s_cmp_ge_u32 s76, s42
	v_add_u32_e32 v205, 0x800, v205
	s_cbranch_scc1 .LBB0_270
	s_waitcnt vmcnt(15)
	v_mov_b32_e32 v145, v129
	v_mov_b32_e32 v144, v128
	s_waitcnt vmcnt(14)
	v_mov_b32_e32 v141, v125
	v_mov_b32_e32 v140, v124
	s_waitcnt vmcnt(13)
	v_mov_b32_e32 v137, v121
	v_mov_b32_e32 v136, v120
	s_waitcnt vmcnt(12)
	v_mov_b32_e32 v133, v117
	v_mov_b32_e32 v132, v116
	s_waitcnt vmcnt(11)
	v_mov_b32_e32 v97, v65
	v_mov_b32_e32 v96, v64
	s_waitcnt vmcnt(10)
	v_mov_b32_e32 v93, v61
	v_mov_b32_e32 v92, v60
	s_waitcnt vmcnt(9)
	v_mov_b32_e32 v73, v57
	v_mov_b32_e32 v72, v56
	s_waitcnt vmcnt(8)
	v_mov_b32_e32 v69, v53
	v_mov_b32_e32 v68, v52
	s_waitcnt vmcnt(7)
	v_mov_b32_e32 v46, v86
	v_mov_b32_e32 v47, v87
	s_waitcnt vmcnt(6)
	v_mov_b32_e32 v42, v82
	v_mov_b32_e32 v43, v83
	s_waitcnt vmcnt(5)
	v_mov_b32_e32 v38, v78
	v_mov_b32_e32 v39, v79
	s_waitcnt vmcnt(4)
	v_mov_b32_e32 v34, v74
	v_mov_b32_e32 v35, v75
	s_waitcnt vmcnt(3)
	v_mov_b32_e32 v30, v110
	v_mov_b32_e32 v31, v111
	s_waitcnt vmcnt(2)
	v_mov_b32_e32 v26, v106
	v_mov_b32_e32 v27, v107
	s_waitcnt vmcnt(1)
	v_mov_b32_e32 v22, v102
	v_mov_b32_e32 v23, v103
	s_waitcnt vmcnt(0)
	v_mov_b32_e32 v18, v98
	v_mov_b32_e32 v19, v99
	v_mov_b32_e32 v143, v127
	v_mov_b32_e32 v142, v126
	v_mov_b32_e32 v139, v123
	v_mov_b32_e32 v138, v122
	v_mov_b32_e32 v135, v119
	v_mov_b32_e32 v134, v118
	v_mov_b32_e32 v131, v115
	v_mov_b32_e32 v130, v114
	v_mov_b32_e32 v95, v63
	v_mov_b32_e32 v94, v62
	v_mov_b32_e32 v91, v59
	v_mov_b32_e32 v90, v58
	v_mov_b32_e32 v71, v55
	v_mov_b32_e32 v70, v54
	v_mov_b32_e32 v67, v51
	v_mov_b32_e32 v66, v50
	v_mov_b32_e32 v48, v88
	v_mov_b32_e32 v49, v89
	v_mov_b32_e32 v44, v84
	v_mov_b32_e32 v45, v85
	v_mov_b32_e32 v40, v80
	v_mov_b32_e32 v41, v81
	v_mov_b32_e32 v36, v76
	v_mov_b32_e32 v37, v77
	v_mov_b32_e32 v32, v112
	v_mov_b32_e32 v33, v113
	v_mov_b32_e32 v28, v108
	v_mov_b32_e32 v29, v109
	v_mov_b32_e32 v24, v104
	v_mov_b32_e32 v25, v105
	v_mov_b32_e32 v20, v100
	v_mov_b32_e32 v21, v101
	s_add_i32 s76, s43, 2
	s_cmp_ge_u32 s76, s42
	s_cbranch_scc0 .LBB0_253
	s_branch .LBB0_254

.LBB0_275:
	v_min_i32_e32 v240, s50, v103
	v_lshl_add_u32 v240, v240, 5, v202
	ds_read_b128 v[208:211], v240
	v_add_u32_e32 v241, 4, v103
	v_min_i32_e32 v241, s50, v241
	v_lshl_add_u32 v241, v241, 5, v202
	ds_read_b128 v[212:215], v241
	v_add_u32_e32 v242, 8, v103
	v_min_i32_e32 v242, s50, v242
	v_lshl_add_u32 v242, v242, 5, v202
	ds_read_b128 v[216:219], v242
	v_add_u32_e32 v243, 12, v103
	v_min_i32_e32 v243, s50, v243
	v_lshl_add_u32 v243, v243, 5, v202
	ds_read_b128 v[220:223], v243
	v_add_u32_e32 v244, 16, v103
	v_min_i32_e32 v244, s50, v244
	v_lshl_add_u32 v244, v244, 5, v202
	ds_read_b128 v[224:227], v244
	v_add_u32_e32 v245, 20, v103
	v_min_i32_e32 v245, s50, v245
	v_lshl_add_u32 v245, v245, 5, v202
	ds_read_b128 v[228:231], v245
	v_add_u32_e32 v246, 24, v103
	v_min_i32_e32 v246, s50, v246
	v_lshl_add_u32 v246, v246, 5, v202
	ds_read_b128 v[232:235], v246
	v_add_u32_e32 v247, 28, v103
	v_min_i32_e32 v247, s50, v247
	v_lshl_add_u32 v247, v247, 5, v202
	ds_read_b128 v[236:239], v247
	v_cmp_lt_u32_e32 vcc, s50, v103
	v_lshlrev_b32_e32 v114, 16, v62
	v_and_b32_e32 v115, 0xffff0000, v62
	v_lshlrev_b32_e32 v62, 16, v63
	s_waitcnt lgkmcnt(7)
	v_cndmask_b32_e64 v110, v211, 0, vcc
	v_cndmask_b32_e64 v108, v210, 0, vcc
	v_cndmask_b32_e64 v112, v209, 0, vcc
	v_cndmask_b32_e64 v106, v208, 0, vcc
	v_and_b32_e32 v63, 0xffff0000, v63
	v_pk_fma_f32 v[88:89], v[106:107], v[62:63], v[88:89] op_sel_hi:[0,1,1]
	v_pk_fma_f32 v[86:87], v[112:113], v[62:63], v[86:87] op_sel_hi:[0,1,1]
	v_pk_fma_f32 v[84:85], v[108:109], v[62:63], v[84:85] op_sel_hi:[0,1,1]
	v_pk_fma_f32 v[82:83], v[110:111], v[62:63], v[82:83] op_sel_hi:[0,1,1]
	v_add_u32_e32 v62, 4, v103
	v_cmp_lt_u32_e32 vcc, s50, v62
	v_lshlrev_b32_e32 v116, 16, v64
	v_and_b32_e32 v117, 0xffff0000, v64
	v_lshlrev_b32_e32 v64, 16, v65
	v_and_b32_e32 v65, 0xffff0000, v65
	v_pk_fma_f32 v[72:73], v[106:107], v[64:65], v[72:73] op_sel_hi:[0,1,1]
	v_pk_fma_f32 v[70:71], v[112:113], v[64:65], v[70:71] op_sel_hi:[0,1,1]
	v_pk_fma_f32 v[68:69], v[108:109], v[64:65], v[68:69] op_sel_hi:[0,1,1]
	v_pk_fma_f32 v[66:67], v[110:111], v[64:65], v[66:67] op_sel_hi:[0,1,1]
	v_pk_fma_f32 v[92:93], v[106:107], v[114:115], v[92:93] op_sel_hi:[0,1,1]
	v_pk_fma_f32 v[80:81], v[106:107], v[116:117], v[80:81] op_sel_hi:[0,1,1]
	v_pk_fma_f32 v[94:95], v[108:109], v[114:115], v[94:95] op_sel_hi:[0,1,1]
	v_pk_fma_f32 v[74:75], v[108:109], v[116:117], v[74:75] op_sel_hi:[0,1,1]
	v_pk_fma_f32 v[90:91], v[110:111], v[114:115], v[90:91] op_sel_hi:[0,1,1]
	v_pk_fma_f32 v[76:77], v[110:111], v[116:117], v[76:77] op_sel_hi:[0,1,1]
	s_waitcnt lgkmcnt(6)
	v_cndmask_b32_e64 v106, v215, 0, vcc
	v_cndmask_b32_e64 v64, v214, 0, vcc
	v_cndmask_b32_e64 v108, v213, 0, vcc
	v_cndmask_b32_e64 v62, v212, 0, vcc
	v_lshlrev_b32_e32 v110, 16, v58
	v_and_b32_e32 v111, 0xffff0000, v58
	v_lshlrev_b32_e32 v58, 16, v59
	v_and_b32_e32 v59, 0xffff0000, v59
	v_pk_fma_f32 v[88:89], v[62:63], v[58:59], v[88:89] op_sel_hi:[0,1,1]
	v_pk_fma_f32 v[86:87], v[108:109], v[58:59], v[86:87] op_sel_hi:[0,1,1]
	v_pk_fma_f32 v[84:85], v[64:65], v[58:59], v[84:85] op_sel_hi:[0,1,1]
	v_pk_fma_f32 v[82:83], v[106:107], v[58:59], v[82:83] op_sel_hi:[0,1,1]
	v_add_u32_e32 v58, 8, v103
	v_cmp_lt_u32_e32 vcc, s50, v58
	v_pk_fma_f32 v[96:97], v[112:113], v[114:115], v[96:97] op_sel_hi:[0,1,1]
	v_pk_fma_f32 v[78:79], v[112:113], v[116:117], v[78:79] op_sel_hi:[0,1,1]
	v_lshlrev_b32_e32 v112, 16, v60
	v_and_b32_e32 v113, 0xffff0000, v60
	v_lshlrev_b32_e32 v60, 16, v61
	v_and_b32_e32 v61, 0xffff0000, v61
	v_pk_fma_f32 v[72:73], v[62:63], v[60:61], v[72:73] op_sel_hi:[0,1,1]
	v_pk_fma_f32 v[70:71], v[108:109], v[60:61], v[70:71] op_sel_hi:[0,1,1]
	v_pk_fma_f32 v[68:69], v[64:65], v[60:61], v[68:69] op_sel_hi:[0,1,1]
	v_pk_fma_f32 v[66:67], v[106:107], v[60:61], v[66:67] op_sel_hi:[0,1,1]
	v_pk_fma_f32 v[80:81], v[62:63], v[112:113], v[80:81] op_sel_hi:[0,1,1]
	v_pk_fma_f32 v[62:63], v[62:63], v[110:111], v[92:93] op_sel_hi:[0,1,1]
	v_pk_fma_f32 v[92:93], v[108:109], v[110:111], v[96:97] op_sel_hi:[0,1,1]
	v_pk_fma_f32 v[74:75], v[64:65], v[112:113], v[74:75] op_sel_hi:[0,1,1]
	v_pk_fma_f32 v[64:65], v[64:65], v[110:111], v[94:95] op_sel_hi:[0,1,1]
	v_pk_fma_f32 v[76:77], v[106:107], v[112:113], v[76:77] op_sel_hi:[0,1,1]
	v_pk_fma_f32 v[90:91], v[106:107], v[110:111], v[90:91] op_sel_hi:[0,1,1]
	s_waitcnt lgkmcnt(5)
	v_cndmask_b32_e64 v94, v219, 0, vcc
	v_cndmask_b32_e64 v60, v218, 0, vcc
	v_cndmask_b32_e64 v96, v217, 0, vcc
	v_cndmask_b32_e64 v58, v216, 0, vcc
	v_lshlrev_b32_e32 v106, 16, v54
	v_and_b32_e32 v107, 0xffff0000, v54
	v_lshlrev_b32_e32 v54, 16, v55
	v_and_b32_e32 v55, 0xffff0000, v55
	v_pk_fma_f32 v[88:89], v[58:59], v[54:55], v[88:89] op_sel_hi:[0,1,1]
	v_pk_fma_f32 v[86:87], v[96:97], v[54:55], v[86:87] op_sel_hi:[0,1,1]
	v_pk_fma_f32 v[84:85], v[60:61], v[54:55], v[84:85] op_sel_hi:[0,1,1]
	v_pk_fma_f32 v[82:83], v[94:95], v[54:55], v[82:83] op_sel_hi:[0,1,1]
	v_add_u32_e32 v54, 12, v103
	v_cmp_lt_u32_e32 vcc, s50, v54
	v_pk_fma_f32 v[78:79], v[108:109], v[112:113], v[78:79] op_sel_hi:[0,1,1]
	v_lshlrev_b32_e32 v108, 16, v56
	v_and_b32_e32 v109, 0xffff0000, v56
	v_lshlrev_b32_e32 v56, 16, v57
	v_and_b32_e32 v57, 0xffff0000, v57
	v_pk_fma_f32 v[62:63], v[58:59], v[106:107], v[62:63] op_sel_hi:[0,1,1]
	v_pk_fma_f32 v[80:81], v[58:59], v[108:109], v[80:81] op_sel_hi:[0,1,1]
	v_pk_fma_f32 v[58:59], v[58:59], v[56:57], v[72:73] op_sel_hi:[0,1,1]
	v_pk_fma_f32 v[70:71], v[96:97], v[56:57], v[70:71] op_sel_hi:[0,1,1]
	v_pk_fma_f32 v[64:65], v[60:61], v[106:107], v[64:65] op_sel_hi:[0,1,1]
	v_pk_fma_f32 v[74:75], v[60:61], v[108:109], v[74:75] op_sel_hi:[0,1,1]
	v_pk_fma_f32 v[60:61], v[60:61], v[56:57], v[68:69] op_sel_hi:[0,1,1]
	v_pk_fma_f32 v[66:67], v[94:95], v[56:57], v[66:67] op_sel_hi:[0,1,1]
	v_pk_fma_f32 v[72:73], v[96:97], v[106:107], v[92:93] op_sel_hi:[0,1,1]
	v_pk_fma_f32 v[78:79], v[96:97], v[108:109], v[78:79] op_sel_hi:[0,1,1]
	v_pk_fma_f32 v[68:69], v[94:95], v[106:107], v[90:91] op_sel_hi:[0,1,1]
	v_pk_fma_f32 v[76:77], v[94:95], v[108:109], v[76:77] op_sel_hi:[0,1,1]
	s_waitcnt lgkmcnt(4)
	v_cndmask_b32_e64 v90, v223, 0, vcc
	v_cndmask_b32_e64 v56, v222, 0, vcc
	v_cndmask_b32_e64 v92, v221, 0, vcc
	v_cndmask_b32_e64 v54, v220, 0, vcc
	v_lshlrev_b32_e32 v94, 16, v50
	v_and_b32_e32 v95, 0xffff0000, v50
	v_lshlrev_b32_e32 v50, 16, v51
	v_and_b32_e32 v51, 0xffff0000, v51
	v_lshlrev_b32_e32 v96, 16, v52
	v_and_b32_e32 v97, 0xffff0000, v52
	v_lshlrev_b32_e32 v52, 16, v53
	v_and_b32_e32 v53, 0xffff0000, v53
	v_pk_fma_f32 v[58:59], v[54:55], v[52:53], v[58:59] op_sel_hi:[0,1,1]
	v_pk_fma_f32 v[80:81], v[54:55], v[96:97], v[80:81] op_sel_hi:[0,1,1]
	v_pk_fma_f32 v[88:89], v[54:55], v[50:51], v[88:89] op_sel_hi:[0,1,1]
	v_pk_fma_f32 v[54:55], v[54:55], v[94:95], v[62:63] op_sel_hi:[0,1,1]
	v_pk_fma_f32 v[62:63], v[92:93], v[52:53], v[70:71] op_sel_hi:[0,1,1]
	v_pk_fma_f32 v[70:71], v[92:93], v[96:97], v[78:79] op_sel_hi:[0,1,1]
	v_pk_fma_f32 v[78:79], v[92:93], v[50:51], v[86:87] op_sel_hi:[0,1,1]
	v_pk_fma_f32 v[60:61], v[56:57], v[52:53], v[60:61] op_sel_hi:[0,1,1]
	v_pk_fma_f32 v[74:75], v[56:57], v[96:97], v[74:75] op_sel_hi:[0,1,1]
	v_pk_fma_f32 v[84:85], v[56:57], v[50:51], v[84:85] op_sel_hi:[0,1,1]
	v_pk_fma_f32 v[56:57], v[56:57], v[94:95], v[64:65] op_sel_hi:[0,1,1]
	v_pk_fma_f32 v[64:65], v[90:91], v[52:53], v[66:67] op_sel_hi:[0,1,1]
	v_pk_fma_f32 v[66:67], v[90:91], v[96:97], v[76:77] op_sel_hi:[0,1,1]
	v_pk_fma_f32 v[76:77], v[90:91], v[50:51], v[82:83] op_sel_hi:[0,1,1]
	v_add_u32_e32 v50, 16, v103
	v_cmp_lt_u32_e32 vcc, s50, v50
	v_pk_fma_f32 v[72:73], v[92:93], v[94:95], v[72:73] op_sel_hi:[0,1,1]
	v_pk_fma_f32 v[68:69], v[90:91], v[94:95], v[68:69] op_sel_hi:[0,1,1]
	v_lshlrev_b32_e32 v90, 16, v46
	v_and_b32_e32 v91, 0xffff0000, v46
	s_waitcnt lgkmcnt(3)
	v_cndmask_b32_e64 v82, v227, 0, vcc
	v_cndmask_b32_e64 v52, v226, 0, vcc
	v_cndmask_b32_e64 v86, v225, 0, vcc
	v_cndmask_b32_e64 v50, v224, 0, vcc
	v_lshlrev_b32_e32 v46, 16, v47
	v_and_b32_e32 v47, 0xffff0000, v47
	v_lshlrev_b32_e32 v92, 16, v48
	v_and_b32_e32 v93, 0xffff0000, v48
	v_lshlrev_b32_e32 v48, 16, v49
	v_and_b32_e32 v49, 0xffff0000, v49
	v_pk_fma_f32 v[54:55], v[50:51], v[90:91], v[54:55] op_sel_hi:[0,1,1]
	v_pk_fma_f32 v[88:89], v[50:51], v[46:47], v[88:89] op_sel_hi:[0,1,1]
	v_pk_fma_f32 v[80:81], v[50:51], v[92:93], v[80:81] op_sel_hi:[0,1,1]
	v_pk_fma_f32 v[50:51], v[50:51], v[48:49], v[58:59] op_sel_hi:[0,1,1]
	v_pk_fma_f32 v[58:59], v[86:87], v[90:91], v[72:73] op_sel_hi:[0,1,1]
	v_pk_fma_f32 v[72:73], v[86:87], v[46:47], v[78:79] op_sel_hi:[0,1,1]
	v_pk_fma_f32 v[56:57], v[52:53], v[90:91], v[56:57] op_sel_hi:[0,1,1]
	v_pk_fma_f32 v[78:79], v[52:53], v[46:47], v[84:85] op_sel_hi:[0,1,1]
	v_pk_fma_f32 v[74:75], v[52:53], v[92:93], v[74:75] op_sel_hi:[0,1,1]
	v_pk_fma_f32 v[52:53], v[52:53], v[48:49], v[60:61] op_sel_hi:[0,1,1]
	v_pk_fma_f32 v[60:61], v[82:83], v[90:91], v[68:69] op_sel_hi:[0,1,1]
	v_pk_fma_f32 v[68:69], v[82:83], v[46:47], v[76:77] op_sel_hi:[0,1,1]
	v_add_u32_e32 v46, 20, v103
	v_cmp_lt_u32_e32 vcc, s50, v46
	v_pk_fma_f32 v[62:63], v[86:87], v[48:49], v[62:63] op_sel_hi:[0,1,1]
	v_pk_fma_f32 v[64:65], v[82:83], v[48:49], v[64:65] op_sel_hi:[0,1,1]
	v_pk_fma_f32 v[70:71], v[86:87], v[92:93], v[70:71] op_sel_hi:[0,1,1]
	v_pk_fma_f32 v[66:67], v[82:83], v[92:93], v[66:67] op_sel_hi:[0,1,1]
	v_lshlrev_b32_e32 v84, 16, v10
	v_and_b32_e32 v85, 0xffff0000, v10
	s_waitcnt lgkmcnt(2)
	v_cndmask_b32_e64 v76, v231, 0, vcc
	v_cndmask_b32_e64 v48, v230, 0, vcc
	v_cndmask_b32_e64 v82, v229, 0, vcc
	v_cndmask_b32_e64 v46, v228, 0, vcc
	v_lshlrev_b32_e32 v10, 16, v11
	v_and_b32_e32 v11, 0xffff0000, v11
	v_lshlrev_b32_e32 v86, 16, v12
	v_and_b32_e32 v87, 0xffff0000, v12
	v_lshlrev_b32_e32 v12, 16, v13
	v_and_b32_e32 v13, 0xffff0000, v13
	v_pk_fma_f32 v[50:51], v[46:47], v[12:13], v[50:51] op_sel_hi:[0,1,1]
	v_pk_fma_f32 v[80:81], v[46:47], v[86:87], v[80:81] op_sel_hi:[0,1,1]
	v_pk_fma_f32 v[88:89], v[46:47], v[10:11], v[88:89] op_sel_hi:[0,1,1]
	v_pk_fma_f32 v[46:47], v[46:47], v[84:85], v[54:55] op_sel_hi:[0,1,1]
	v_pk_fma_f32 v[54:55], v[82:83], v[12:13], v[62:63] op_sel_hi:[0,1,1]
	v_pk_fma_f32 v[62:63], v[82:83], v[86:87], v[70:71] op_sel_hi:[0,1,1]
	v_pk_fma_f32 v[70:71], v[82:83], v[10:11], v[72:73] op_sel_hi:[0,1,1]
	v_pk_fma_f32 v[52:53], v[48:49], v[12:13], v[52:53] op_sel_hi:[0,1,1]
	v_pk_fma_f32 v[72:73], v[48:49], v[86:87], v[74:75] op_sel_hi:[0,1,1]
	v_pk_fma_f32 v[74:75], v[48:49], v[10:11], v[78:79] op_sel_hi:[0,1,1]
	v_pk_fma_f32 v[48:49], v[48:49], v[84:85], v[56:57] op_sel_hi:[0,1,1]
	v_pk_fma_f32 v[56:57], v[76:77], v[12:13], v[64:65] op_sel_hi:[0,1,1]
	v_pk_fma_f32 v[64:65], v[76:77], v[86:87], v[66:67] op_sel_hi:[0,1,1]
	v_pk_fma_f32 v[66:67], v[76:77], v[10:11], v[68:69] op_sel_hi:[0,1,1]
	v_add_u32_e32 v10, 24, v103
	v_cmp_lt_u32_e32 vcc, s50, v10
	v_pk_fma_f32 v[58:59], v[82:83], v[84:85], v[58:59] op_sel_hi:[0,1,1]
	v_pk_fma_f32 v[60:61], v[76:77], v[84:85], v[60:61] op_sel_hi:[0,1,1]
	v_lshlrev_b32_e32 v78, 16, v6
	v_and_b32_e32 v79, 0xffff0000, v6
	s_waitcnt lgkmcnt(1)
	v_cndmask_b32_e64 v68, v235, 0, vcc
	v_cndmask_b32_e64 v12, v234, 0, vcc
	v_cndmask_b32_e64 v76, v233, 0, vcc
	v_cndmask_b32_e64 v10, v232, 0, vcc
	v_lshlrev_b32_e32 v6, 16, v7
	v_and_b32_e32 v7, 0xffff0000, v7
	v_lshlrev_b32_e32 v82, 16, v8
	v_and_b32_e32 v83, 0xffff0000, v8
	v_lshlrev_b32_e32 v8, 16, v9
	v_and_b32_e32 v9, 0xffff0000, v9
	v_pk_fma_f32 v[46:47], v[10:11], v[78:79], v[46:47] op_sel_hi:[0,1,1]
	v_pk_fma_f32 v[84:85], v[10:11], v[6:7], v[88:89] op_sel_hi:[0,1,1]
	v_pk_fma_f32 v[80:81], v[10:11], v[82:83], v[80:81] op_sel_hi:[0,1,1]
	v_pk_fma_f32 v[10:11], v[10:11], v[8:9], v[50:51] op_sel_hi:[0,1,1]
	v_pk_fma_f32 v[50:51], v[76:77], v[78:79], v[58:59] op_sel_hi:[0,1,1]
	v_pk_fma_f32 v[58:59], v[76:77], v[6:7], v[70:71] op_sel_hi:[0,1,1]
	v_pk_fma_f32 v[62:63], v[76:77], v[82:83], v[62:63] op_sel_hi:[0,1,1]
	v_pk_fma_f32 v[54:55], v[76:77], v[8:9], v[54:55] op_sel_hi:[0,1,1]
	v_pk_fma_f32 v[48:49], v[12:13], v[78:79], v[48:49] op_sel_hi:[0,1,1]
	v_pk_fma_f32 v[76:77], v[12:13], v[6:7], v[74:75] op_sel_hi:[0,1,1]
	v_pk_fma_f32 v[74:75], v[12:13], v[82:83], v[72:73] op_sel_hi:[0,1,1]
	v_pk_fma_f32 v[12:13], v[12:13], v[8:9], v[52:53] op_sel_hi:[0,1,1]
	v_pk_fma_f32 v[52:53], v[68:69], v[78:79], v[60:61] op_sel_hi:[0,1,1]
	v_pk_fma_f32 v[60:61], v[68:69], v[6:7], v[66:67] op_sel_hi:[0,1,1]
	v_add_u32_e32 v6, 28, v103
	v_cmp_lt_u32_e32 vcc, s50, v6
	v_pk_fma_f32 v[56:57], v[68:69], v[8:9], v[56:57] op_sel_hi:[0,1,1]
	v_pk_fma_f32 v[64:65], v[68:69], v[82:83], v[64:65] op_sel_hi:[0,1,1]
	v_lshlrev_b32_e32 v106, 16, v2
	v_and_b32_e32 v107, 0xffff0000, v2
	v_lshlrev_b32_e32 v2, 16, v3
	s_waitcnt lgkmcnt(0)
	v_cndmask_b32_e64 v90, v239, 0, vcc
	v_cndmask_b32_e64 v8, v238, 0, vcc
	v_cndmask_b32_e64 v66, v237, 0, vcc
	v_cndmask_b32_e64 v6, v236, 0, vcc
	v_and_b32_e32 v3, 0xffff0000, v3
	v_lshlrev_b32_e32 v82, 16, v4
	v_and_b32_e32 v83, 0xffff0000, v4
	v_lshlrev_b32_e32 v4, 16, v5
	v_and_b32_e32 v5, 0xffff0000, v5
	v_pk_fma_f32 v[72:73], v[6:7], v[4:5], v[10:11] op_sel_hi:[0,1,1]
	v_pk_fma_f32 v[80:81], v[6:7], v[82:83], v[80:81] op_sel_hi:[0,1,1]
	v_pk_fma_f32 v[88:89], v[6:7], v[2:3], v[84:85] op_sel_hi:[0,1,1]
	v_pk_fma_f32 v[92:93], v[6:7], v[106:107], v[46:47] op_sel_hi:[0,1,1]
	v_pk_fma_f32 v[70:71], v[66:67], v[4:5], v[54:55] op_sel_hi:[0,1,1]
	v_pk_fma_f32 v[78:79], v[66:67], v[82:83], v[62:63] op_sel_hi:[0,1,1]
	v_pk_fma_f32 v[86:87], v[66:67], v[2:3], v[58:59] op_sel_hi:[0,1,1]
	v_pk_fma_f32 v[96:97], v[66:67], v[106:107], v[50:51] op_sel_hi:[0,1,1]
	v_pk_fma_f32 v[68:69], v[8:9], v[4:5], v[12:13] op_sel_hi:[0,1,1]
	v_pk_fma_f32 v[74:75], v[8:9], v[82:83], v[74:75] op_sel_hi:[0,1,1]
	v_pk_fma_f32 v[84:85], v[8:9], v[2:3], v[76:77] op_sel_hi:[0,1,1]
	v_pk_fma_f32 v[94:95], v[8:9], v[106:107], v[48:49] op_sel_hi:[0,1,1]
	v_pk_fma_f32 v[66:67], v[90:91], v[4:5], v[56:57] op_sel_hi:[0,1,1]
	v_pk_fma_f32 v[76:77], v[90:91], v[82:83], v[64:65] op_sel_hi:[0,1,1]
	v_pk_fma_f32 v[82:83], v[90:91], v[2:3], v[60:61] op_sel_hi:[0,1,1]
	v_pk_fma_f32 v[90:91], v[90:91], v[106:107], v[52:53] op_sel_hi:[0,1,1]
	s_add_i32 s76, s76, 8
	s_andn2_b64 vcc, exec, s[34:35]
	v_mov_b32_e32 v103, v104
	s_waitcnt vmcnt(0)
	v_mov_b32_e32 v2, v42
	v_mov_b32_e32 v3, v43
	v_mov_b32_e32 v4, v44
	v_mov_b32_e32 v5, v45
	v_mov_b32_e32 v6, v38
	v_mov_b32_e32 v7, v39
	v_mov_b32_e32 v8, v40
	v_mov_b32_e32 v9, v41
	v_mov_b32_e32 v10, v34
	v_mov_b32_e32 v11, v35
	v_mov_b32_e32 v12, v36
	v_mov_b32_e32 v13, v37
	v_mov_b32_e32 v47, v31
	v_mov_b32_e32 v46, v30
	v_mov_b32_e32 v49, v33
	v_mov_b32_e32 v48, v32
	v_mov_b32_e32 v51, v27
	v_mov_b32_e32 v50, v26
	v_mov_b32_e32 v53, v29
	v_mov_b32_e32 v52, v28
	v_mov_b32_e32 v55, v23
	v_mov_b32_e32 v54, v22
	v_mov_b32_e32 v57, v25
	v_mov_b32_e32 v56, v24
	v_mov_b32_e32 v59, v19
	v_mov_b32_e32 v58, v18
	v_mov_b32_e32 v61, v21
	v_mov_b32_e32 v60, v20
	v_mov_b32_e32 v63, v15
	v_mov_b32_e32 v62, v14
	v_mov_b32_e32 v65, v17
	v_mov_b32_e32 v64, v16
	s_cbranch_vccz .LBB0_241
